# v20 + hand-written final RMSNorm loop: hipcc had serialised its loads (load-wait-copy x4 per step); now one row per step, three rows of loads in flight, 1 KiB-contiguous stores
# baseline (speedup 1.0000x reference)
; __global__ void __launch_bounds__(NTHREADS, 2) fwd(Args a) {
;     ...
;     if (IN(NPHASE - 1)) {
;         const int gw = r * NWAVES + wave, NGW = GS * NWAVES; const size_t tb = (size_t)b * SEQ;
;         const float* fw = a.in[16]; const u64* rs6 = (const u64*)(a.ws + WS_ROWSS) + (size_t)6 * M + tb; const bf16* XN = (const bf16*)(a.ws + WS_XN) + tb * D; float* outb = a.out + tb * D;
;         f32x4 wv[2][2];
; #pragma unroll
;         for (int j = 0; j < 2; ++j) { wv[j][0] = *((const f32x4*)fw + 2 * (lane + 64 * j)); wv[j][1] = *((const f32x4*)fw + 2 * (lane + 64 * j) + 1); }
;         for (int m = gw; m < SEQ; m += 2 * NGW) {
;             const int m1 = m + NGW; const bool two = m1 < SEQ;
;             u32x4 xv[2][2]; u64 sv[2];
;             sv[0] = rs6[m]; sv[1] = two ? rs6[m1] : sv[0];
; #pragma unroll
;             for (int j = 0; j < 2; ++j) { xv[0][j] = *((const u32x4*)(XN + (size_t)m * D) + lane + 64 * j); xv[1][j] = two ? *((const u32x4*)(XN + (size_t)m1 * D) + lane + 64 * j) : xv[0][j]; }
.LBB0_1431:
	s_cmp_gt_i32 s52, 19
	s_cselect_b64 s[0:1], -1, 0
	s_xor_b64 s[2:3], s[2:3], -1
	s_or_b64 s[0:1], s[0:1], s[2:3]
	s_and_b64 vcc, exec, s[0:1]
	s_cbranch_vccnz .LBB0_1445
	s_cmpk_gt_i32 s38, 0xfff
	s_cbranch_scc1 .LBB0_1445
	v_readlane_b32 s6, v230, 0
	v_readlane_b32 s7, v230, 1
	v_readlane_b32 s4, v230, 2
	v_readlane_b32 s5, v230, 3
	v_readlane_b32 s0, v230, 6
	v_readlane_b32 s1, v230, 7
	s_waitcnt lgkmcnt(0)
	s_nop 4
	s_add_u32 s0, s34, s0
	s_addc_u32 s1, s35, s1
	s_add_u32 s12, s0, 0x280000
	s_addc_u32 s13, s1, 0
	s_lshl_b64 s[0:1], s[40:41], 2
	s_add_u32 s4, s4, s0
	s_addc_u32 s5, s5, s1
	v_mov_b32_e32 v1, 0
	v_lshlrev_b32_e32 v2, 3, v200
	v_lshlrev_b32_e32 v3, 4, v200
	v_mov_b32_e32 v4, 0x358637bd
	v_mov_b32_e32 v65, 0
	global_load_dwordx4 v[8:11], v3, s[6:7] offset:0
	global_load_dwordx4 v[12:15], v3, s[6:7] offset:1024
	global_load_dwordx4 v[16:19], v3, s[6:7] offset:2048
	global_load_dwordx4 v[20:23], v3, s[6:7] offset:3072
	s_waitcnt vmcnt(0)
	s_lshl_b32 s14, s38, 11
	s_add_u32 s14, s22, s14
	s_addc_u32 s15, s23, 0
	s_lshl_b32 s16, s38, 3
	s_add_u32 s16, s12, s16
	s_addc_u32 s17, s13, 0
	global_load_dwordx2 v[24:25], v1, s[16:17]
	global_load_dwordx2 v[26:27], v2, s[14:15] offset:0
	global_load_dwordx2 v[28:29], v2, s[14:15] offset:512
	global_load_dwordx2 v[30:31], v2, s[14:15] offset:1024
	global_load_dwordx2 v[32:33], v2, s[14:15] offset:1536
	s_add_u32 s20, s38, s36
	s_cmp_lt_u32 s20, 0x1000
	s_cbranch_scc0 .Lfn_a
	s_lshl_b32 s14, s20, 11
	s_add_u32 s14, s22, s14
	s_addc_u32 s15, s23, 0
	s_lshl_b32 s16, s20, 3
	s_add_u32 s16, s12, s16
	s_addc_u32 s17, s13, 0
	global_load_dwordx2 v[36:37], v1, s[16:17]
	global_load_dwordx2 v[38:39], v2, s[14:15] offset:0
	global_load_dwordx2 v[40:41], v2, s[14:15] offset:512
	global_load_dwordx2 v[42:43], v2, s[14:15] offset:1024
	global_load_dwordx2 v[44:45], v2, s[14:15] offset:1536
.Lfn_a:
	s_lshl_b32 s20, s36, 1
	s_add_u32 s20, s38, s20
	s_cmp_lt_u32 s20, 0x1000
	s_cbranch_scc0 .Lfn_a_t
	s_lshl_b32 s14, s20, 11
	s_add_u32 s14, s22, s14
	s_addc_u32 s15, s23, 0
	s_lshl_b32 s16, s20, 3
	s_add_u32 s16, s12, s16
	s_addc_u32 s17, s13, 0
	global_load_dwordx2 v[48:49], v1, s[16:17]
	global_load_dwordx2 v[50:51], v2, s[14:15] offset:0
	global_load_dwordx2 v[52:53], v2, s[14:15] offset:512
	global_load_dwordx2 v[54:55], v2, s[14:15] offset:1024
	global_load_dwordx2 v[56:57], v2, s[14:15] offset:1536
	s_waitcnt vmcnt(10)
	s_branch .Lfn_a_p

; __device__ __forceinline__ float ss_val(u64 v) { return (float)v * (1.0f / 1099511627776.0f); }
; __global__ void __launch_bounds__(NTHREADS, 2) fwd(Args a) {
;     ...
;         for (int m = gw; m < SEQ; m += 2 * NGW) {
;             const int m1 = m + NGW; const bool two = m1 < SEQ;
;             u32x4 xv[2][2]; u64 sv[2];
;             sv[0] = rs6[m]; sv[1] = two ? rs6[m1] : sv[0];
; #pragma unroll
;             for (int j = 0; j < 2; ++j) { xv[0][j] = *((const u32x4*)(XN + (size_t)m * D) + lane + 64 * j); xv[1][j] = two ? *((const u32x4*)(XN + (size_t)m1 * D) + lane + 64 * j) : xv[0][j]; }
;     ...
;             for (int r2 = 0; r2 < 2; ++r2) {
;                 if (r2 == 1 && !two) break;
;                 const float rs = __builtin_amdgcn_rsqf(ss_val(sv[r2]) * (1.f / D) + EPS);
;                 f32x4* orow = (f32x4*)(outb + (size_t)(r2 ? m1 : m) * D);
; #pragma unroll
;                 for (int j = 0; j < 2; ++j) {
;                     const u32x4 x4 = xv[r2][j]; const f32x4 w0 = wv[j][0], w1 = wv[j][1];
;                     f32x4 o0, o1;
;                     o0[0] = bf_lo(x4[0]) * rs * w0[0]; o0[1] = bf_hi(x4[0]) * rs * w0[1]; o0[2] = bf_lo(x4[1]) * rs * w0[2]; o0[3] = bf_hi(x4[1]) * rs * w0[3];
;                     o1[0] = bf_lo(x4[2]) * rs * w1[0]; o1[1] = bf_hi(x4[2]) * rs * w1[1]; o1[2] = bf_lo(x4[3]) * rs * w1[2]; o1[3] = bf_hi(x4[3]) * rs * w1[3];
;                     orow[2 * (lane + 64 * j)] = o0; orow[2 * (lane + 64 * j) + 1] = o1;
;                 }
;             }
;         }
.Lfn_a_p:
	s_lshl_b32 s18, s38, 12
	s_add_u32 s18, s4, s18
	s_addc_u32 s19, s5, 0
	v_cvt_f32_u32_e32 v66, v24
	v_cvt_f32_u32_e32 v67, v25
	v_fmamk_f32 v66, v67, 0x4f800000, v66
	v_fmamk_f32 v66, v66, 0x26800000, v4
	v_rsq_f32_e32 v64, v66
	v_lshlrev_b32_e32 v60, 16, v26
	v_and_b32_e32 v61, 0xffff0000, v26
	v_lshlrev_b32_e32 v62, 16, v27
	v_and_b32_e32 v63, 0xffff0000, v27
	v_pk_mul_f32 v[60:61], v[64:65], v[60:61] op_sel_hi:[0,1]
	v_pk_mul_f32 v[62:63], v[64:65], v[62:63] op_sel_hi:[0,1]
	v_pk_mul_f32 v[68:69], v[8:9], v[60:61]
	v_pk_mul_f32 v[70:71], v[10:11], v[62:63]
	global_store_dwordx4 v3, v[68:71], s[18:19] offset:0
	v_lshlrev_b32_e32 v60, 16, v28
	v_and_b32_e32 v61, 0xffff0000, v28
	v_lshlrev_b32_e32 v62, 16, v29
	v_and_b32_e32 v63, 0xffff0000, v29
	v_pk_mul_f32 v[60:61], v[64:65], v[60:61] op_sel_hi:[0,1]
	v_pk_mul_f32 v[62:63], v[64:65], v[62:63] op_sel_hi:[0,1]
	v_pk_mul_f32 v[72:73], v[12:13], v[60:61]
	v_pk_mul_f32 v[74:75], v[14:15], v[62:63]
	global_store_dwordx4 v3, v[72:75], s[18:19] offset:1024
	v_lshlrev_b32_e32 v60, 16, v30
	v_and_b32_e32 v61, 0xffff0000, v30
	v_lshlrev_b32_e32 v62, 16, v31
	v_and_b32_e32 v63, 0xffff0000, v31
	v_pk_mul_f32 v[60:61], v[64:65], v[60:61] op_sel_hi:[0,1]
	v_pk_mul_f32 v[62:63], v[64:65], v[62:63] op_sel_hi:[0,1]
	v_pk_mul_f32 v[76:77], v[16:17], v[60:61]
	v_pk_mul_f32 v[78:79], v[18:19], v[62:63]
	global_store_dwordx4 v3, v[76:79], s[18:19] offset:2048
	v_lshlrev_b32_e32 v60, 16, v32
	v_and_b32_e32 v61, 0xffff0000, v32
	v_lshlrev_b32_e32 v62, 16, v33
	v_and_b32_e32 v63, 0xffff0000, v33
	v_pk_mul_f32 v[60:61], v[64:65], v[60:61] op_sel_hi:[0,1]
	v_pk_mul_f32 v[62:63], v[64:65], v[62:63] op_sel_hi:[0,1]
	v_pk_mul_f32 v[80:81], v[20:21], v[60:61]
	v_pk_mul_f32 v[82:83], v[22:23], v[62:63]
	global_store_dwordx4 v3, v[80:83], s[18:19] offset:3072
	s_add_u32 s38, s38, s36
	s_cmp_lt_u32 s38, 0x1000
	s_cbranch_scc0 .LBB0_1445
.Lfn_b:
	s_lshl_b32 s20, s36, 1
	s_add_u32 s20, s38, s20
	s_cmp_lt_u32 s20, 0x1000
	s_cbranch_scc0 .Lfn_b_t
	s_lshl_b32 s14, s20, 11
	s_add_u32 s14, s22, s14
	s_addc_u32 s15, s23, 0
	s_lshl_b32 s16, s20, 3
	s_add_u32 s16, s12, s16
	s_addc_u32 s17, s13, 0
	global_load_dwordx2 v[24:25], v1, s[16:17]
	global_load_dwordx2 v[26:27], v2, s[14:15] offset:0
	global_load_dwordx2 v[28:29], v2, s[14:15] offset:512
	global_load_dwordx2 v[30:31], v2, s[14:15] offset:1024
	global_load_dwordx2 v[32:33], v2, s[14:15] offset:1536
	s_waitcnt vmcnt(14)
	s_branch .Lfn_b_p

; __device__ __forceinline__ float ss_val(u64 v) { return (float)v * (1.0f / 1099511627776.0f); }
; __global__ void __launch_bounds__(NTHREADS, 2) fwd(Args a) {
;     ...
;         for (int m = gw; m < SEQ; m += 2 * NGW) {
;             const int m1 = m + NGW; const bool two = m1 < SEQ;
;             u32x4 xv[2][2]; u64 sv[2];
;             sv[0] = rs6[m]; sv[1] = two ? rs6[m1] : sv[0];
; #pragma unroll
;             for (int j = 0; j < 2; ++j) { xv[0][j] = *((const u32x4*)(XN + (size_t)m * D) + lane + 64 * j); xv[1][j] = two ? *((const u32x4*)(XN + (size_t)m1 * D) + lane + 64 * j) : xv[0][j]; }
;     ...
;             for (int r2 = 0; r2 < 2; ++r2) {
;                 if (r2 == 1 && !two) break;
;                 const float rs = __builtin_amdgcn_rsqf(ss_val(sv[r2]) * (1.f / D) + EPS);
;                 f32x4* orow = (f32x4*)(outb + (size_t)(r2 ? m1 : m) * D);
; #pragma unroll
;                 for (int j = 0; j < 2; ++j) {
;                     const u32x4 x4 = xv[r2][j]; const f32x4 w0 = wv[j][0], w1 = wv[j][1];
;                     f32x4 o0, o1;
;                     o0[0] = bf_lo(x4[0]) * rs * w0[0]; o0[1] = bf_hi(x4[0]) * rs * w0[1]; o0[2] = bf_lo(x4[1]) * rs * w0[2]; o0[3] = bf_hi(x4[1]) * rs * w0[3];
;                     o1[0] = bf_lo(x4[2]) * rs * w1[0]; o1[1] = bf_hi(x4[2]) * rs * w1[1]; o1[2] = bf_lo(x4[3]) * rs * w1[2]; o1[3] = bf_hi(x4[3]) * rs * w1[3];
;                     orow[2 * (lane + 64 * j)] = o0; orow[2 * (lane + 64 * j) + 1] = o1;
;                 }
;             }
;         }
.Lfn_b_p:
	s_lshl_b32 s18, s38, 12
	s_add_u32 s18, s4, s18
	s_addc_u32 s19, s5, 0
	v_cvt_f32_u32_e32 v66, v36
	v_cvt_f32_u32_e32 v67, v37
	v_fmamk_f32 v66, v67, 0x4f800000, v66
	v_fmamk_f32 v66, v66, 0x26800000, v4
	v_rsq_f32_e32 v64, v66
	v_lshlrev_b32_e32 v60, 16, v38
	v_and_b32_e32 v61, 0xffff0000, v38
	v_lshlrev_b32_e32 v62, 16, v39
	v_and_b32_e32 v63, 0xffff0000, v39
	v_pk_mul_f32 v[60:61], v[64:65], v[60:61] op_sel_hi:[0,1]
	v_pk_mul_f32 v[62:63], v[64:65], v[62:63] op_sel_hi:[0,1]
	v_pk_mul_f32 v[68:69], v[8:9], v[60:61]
	v_pk_mul_f32 v[70:71], v[10:11], v[62:63]
	global_store_dwordx4 v3, v[68:71], s[18:19] offset:0
	v_lshlrev_b32_e32 v60, 16, v40
	v_and_b32_e32 v61, 0xffff0000, v40
	v_lshlrev_b32_e32 v62, 16, v41
	v_and_b32_e32 v63, 0xffff0000, v41
	v_pk_mul_f32 v[60:61], v[64:65], v[60:61] op_sel_hi:[0,1]
	v_pk_mul_f32 v[62:63], v[64:65], v[62:63] op_sel_hi:[0,1]
	v_pk_mul_f32 v[72:73], v[12:13], v[60:61]
	v_pk_mul_f32 v[74:75], v[14:15], v[62:63]
	global_store_dwordx4 v3, v[72:75], s[18:19] offset:1024
	v_lshlrev_b32_e32 v60, 16, v42
	v_and_b32_e32 v61, 0xffff0000, v42
	v_lshlrev_b32_e32 v62, 16, v43
	v_and_b32_e32 v63, 0xffff0000, v43
	v_pk_mul_f32 v[60:61], v[64:65], v[60:61] op_sel_hi:[0,1]
	v_pk_mul_f32 v[62:63], v[64:65], v[62:63] op_sel_hi:[0,1]
	v_pk_mul_f32 v[76:77], v[16:17], v[60:61]
	v_pk_mul_f32 v[78:79], v[18:19], v[62:63]
	global_store_dwordx4 v3, v[76:79], s[18:19] offset:2048
	v_lshlrev_b32_e32 v60, 16, v44
	v_and_b32_e32 v61, 0xffff0000, v44
	v_lshlrev_b32_e32 v62, 16, v45
	v_and_b32_e32 v63, 0xffff0000, v45
	v_pk_mul_f32 v[60:61], v[64:65], v[60:61] op_sel_hi:[0,1]
	v_pk_mul_f32 v[62:63], v[64:65], v[62:63] op_sel_hi:[0,1]
	v_pk_mul_f32 v[80:81], v[20:21], v[60:61]
	v_pk_mul_f32 v[82:83], v[22:23], v[62:63]
	global_store_dwordx4 v3, v[80:83], s[18:19] offset:3072
	s_add_u32 s38, s38, s36
	s_cmp_lt_u32 s38, 0x1000
	s_cbranch_scc0 .LBB0_1445
.Lfn_c:
	s_lshl_b32 s20, s36, 1
	s_add_u32 s20, s38, s20
	s_cmp_lt_u32 s20, 0x1000
	s_cbranch_scc0 .Lfn_c_t
	s_lshl_b32 s14, s20, 11
	s_add_u32 s14, s22, s14
	s_addc_u32 s15, s23, 0
	s_lshl_b32 s16, s20, 3
	s_add_u32 s16, s12, s16
	s_addc_u32 s17, s13, 0
	global_load_dwordx2 v[36:37], v1, s[16:17]
	global_load_dwordx2 v[38:39], v2, s[14:15] offset:0
	global_load_dwordx2 v[40:41], v2, s[14:15] offset:512
	global_load_dwordx2 v[42:43], v2, s[14:15] offset:1024
	global_load_dwordx2 v[44:45], v2, s[14:15] offset:1536
	s_waitcnt vmcnt(18)
	s_branch .Lfn_c_p

; __device__ __forceinline__ float ss_val(u64 v) { return (float)v * (1.0f / 1099511627776.0f); }
; __global__ void __launch_bounds__(NTHREADS, 2) fwd(Args a) {
;     ...
;         for (int m = gw; m < SEQ; m += 2 * NGW) {
;             const int m1 = m + NGW; const bool two = m1 < SEQ;
;             u32x4 xv[2][2]; u64 sv[2];
;             sv[0] = rs6[m]; sv[1] = two ? rs6[m1] : sv[0];
; #pragma unroll
;             for (int j = 0; j < 2; ++j) { xv[0][j] = *((const u32x4*)(XN + (size_t)m * D) + lane + 64 * j); xv[1][j] = two ? *((const u32x4*)(XN + (size_t)m1 * D) + lane + 64 * j) : xv[0][j]; }
;     ...
;             for (int r2 = 0; r2 < 2; ++r2) {
;                 if (r2 == 1 && !two) break;
;                 const float rs = __builtin_amdgcn_rsqf(ss_val(sv[r2]) * (1.f / D) + EPS);
;                 f32x4* orow = (f32x4*)(outb + (size_t)(r2 ? m1 : m) * D);
; #pragma unroll
;                 for (int j = 0; j < 2; ++j) {
;                     const u32x4 x4 = xv[r2][j]; const f32x4 w0 = wv[j][0], w1 = wv[j][1];
;                     f32x4 o0, o1;
;                     o0[0] = bf_lo(x4[0]) * rs * w0[0]; o0[1] = bf_hi(x4[0]) * rs * w0[1]; o0[2] = bf_lo(x4[1]) * rs * w0[2]; o0[3] = bf_hi(x4[1]) * rs * w0[3];
;                     o1[0] = bf_lo(x4[2]) * rs * w1[0]; o1[1] = bf_hi(x4[2]) * rs * w1[1]; o1[2] = bf_lo(x4[3]) * rs * w1[2]; o1[3] = bf_hi(x4[3]) * rs * w1[3];
;                     orow[2 * (lane + 64 * j)] = o0; orow[2 * (lane + 64 * j) + 1] = o1;
;                 }
;             }
;         }
.Lfn_c_p:
	s_lshl_b32 s18, s38, 12
	s_add_u32 s18, s4, s18
	s_addc_u32 s19, s5, 0
	v_cvt_f32_u32_e32 v66, v48
	v_cvt_f32_u32_e32 v67, v49
	v_fmamk_f32 v66, v67, 0x4f800000, v66
	v_fmamk_f32 v66, v66, 0x26800000, v4
	v_rsq_f32_e32 v64, v66
	v_lshlrev_b32_e32 v60, 16, v50
	v_and_b32_e32 v61, 0xffff0000, v50
	v_lshlrev_b32_e32 v62, 16, v51
	v_and_b32_e32 v63, 0xffff0000, v51
	v_pk_mul_f32 v[60:61], v[64:65], v[60:61] op_sel_hi:[0,1]
	v_pk_mul_f32 v[62:63], v[64:65], v[62:63] op_sel_hi:[0,1]
	v_pk_mul_f32 v[68:69], v[8:9], v[60:61]
	v_pk_mul_f32 v[70:71], v[10:11], v[62:63]
	global_store_dwordx4 v3, v[68:71], s[18:19] offset:0
	v_lshlrev_b32_e32 v60, 16, v52
	v_and_b32_e32 v61, 0xffff0000, v52
	v_lshlrev_b32_e32 v62, 16, v53
	v_and_b32_e32 v63, 0xffff0000, v53
	v_pk_mul_f32 v[60:61], v[64:65], v[60:61] op_sel_hi:[0,1]
	v_pk_mul_f32 v[62:63], v[64:65], v[62:63] op_sel_hi:[0,1]
	v_pk_mul_f32 v[72:73], v[12:13], v[60:61]
	v_pk_mul_f32 v[74:75], v[14:15], v[62:63]
	global_store_dwordx4 v3, v[72:75], s[18:19] offset:1024
	v_lshlrev_b32_e32 v60, 16, v54
	v_and_b32_e32 v61, 0xffff0000, v54
	v_lshlrev_b32_e32 v62, 16, v55
	v_and_b32_e32 v63, 0xffff0000, v55
	v_pk_mul_f32 v[60:61], v[64:65], v[60:61] op_sel_hi:[0,1]
	v_pk_mul_f32 v[62:63], v[64:65], v[62:63] op_sel_hi:[0,1]
	v_pk_mul_f32 v[76:77], v[16:17], v[60:61]
	v_pk_mul_f32 v[78:79], v[18:19], v[62:63]
	global_store_dwordx4 v3, v[76:79], s[18:19] offset:2048
	v_lshlrev_b32_e32 v60, 16, v56
	v_and_b32_e32 v61, 0xffff0000, v56
	v_lshlrev_b32_e32 v62, 16, v57
	v_and_b32_e32 v63, 0xffff0000, v57
	v_pk_mul_f32 v[60:61], v[64:65], v[60:61] op_sel_hi:[0,1]
	v_pk_mul_f32 v[62:63], v[64:65], v[62:63] op_sel_hi:[0,1]
	v_pk_mul_f32 v[80:81], v[20:21], v[60:61]
	v_pk_mul_f32 v[82:83], v[22:23], v[62:63]
	global_store_dwordx4 v3, v[80:83], s[18:19] offset:3072
	s_add_u32 s38, s38, s36
	s_cmp_lt_u32 s38, 0x1000
	s_cbranch_scc0 .LBB0_1445
.Lfn_d:
	s_lshl_b32 s20, s36, 1
	s_add_u32 s20, s38, s20
	s_cmp_lt_u32 s20, 0x1000
	s_cbranch_scc0 .Lfn_d_t
	s_lshl_b32 s14, s20, 11
	s_add_u32 s14, s22, s14
	s_addc_u32 s15, s23, 0
	s_lshl_b32 s16, s20, 3
	s_add_u32 s16, s12, s16
	s_addc_u32 s17, s13, 0
	global_load_dwordx2 v[48:49], v1, s[16:17]
	global_load_dwordx2 v[50:51], v2, s[14:15] offset:0
	global_load_dwordx2 v[52:53], v2, s[14:15] offset:512
	global_load_dwordx2 v[54:55], v2, s[14:15] offset:1024
	global_load_dwordx2 v[56:57], v2, s[14:15] offset:1536
	s_waitcnt vmcnt(18)
	s_branch .Lfn_d_p

; __global__ void __launch_bounds__(NTHREADS, 2) fwd(Args a) {
;     ...
;         for (int m = gw; m < SEQ; m += 2 * NGW) {
;             const int m1 = m + NGW; const bool two = m1 < SEQ;
;             u32x4 xv[2][2]; u64 sv[2];
;             sv[0] = rs6[m]; sv[1] = two ? rs6[m1] : sv[0];
; #pragma unroll
;             for (int j = 0; j < 2; ++j) { xv[0][j] = *((const u32x4*)(XN + (size_t)m * D) + lane + 64 * j); xv[1][j] = two ? *((const u32x4*)(XN + (size_t)m1 * D) + lane + 64 * j) : xv[0][j]; }
.Lfn_e:
	s_lshl_b32 s20, s36, 1
	s_add_u32 s20, s38, s20
	s_cmp_lt_u32 s20, 0x1000
	s_cbranch_scc0 .Lfn_e_t
	s_lshl_b32 s14, s20, 11
	s_add_u32 s14, s22, s14
	s_addc_u32 s15, s23, 0
	s_lshl_b32 s16, s20, 3
	s_add_u32 s16, s12, s16
	s_addc_u32 s17, s13, 0
	global_load_dwordx2 v[24:25], v1, s[16:17]
	global_load_dwordx2 v[26:27], v2, s[14:15] offset:0
	global_load_dwordx2 v[28:29], v2, s[14:15] offset:512
	global_load_dwordx2 v[30:31], v2, s[14:15] offset:1024
	global_load_dwordx2 v[32:33], v2, s[14:15] offset:1536
	s_waitcnt vmcnt(18)
	s_branch .Lfn_e_p

; __device__ __forceinline__ float ss_val(u64 v) { return (float)v * (1.0f / 1099511627776.0f); }
; __global__ void __launch_bounds__(NTHREADS, 2) fwd(Args a) {
;     ...
;             for (int r2 = 0; r2 < 2; ++r2) {
;                 if (r2 == 1 && !two) break;
;                 const float rs = __builtin_amdgcn_rsqf(ss_val(sv[r2]) * (1.f / D) + EPS);
;                 f32x4* orow = (f32x4*)(outb + (size_t)(r2 ? m1 : m) * D);
; #pragma unroll
;                 for (int j = 0; j < 2; ++j) {
;                     const u32x4 x4 = xv[r2][j]; const f32x4 w0 = wv[j][0], w1 = wv[j][1];
;                     f32x4 o0, o1;
;                     o0[0] = bf_lo(x4[0]) * rs * w0[0]; o0[1] = bf_hi(x4[0]) * rs * w0[1]; o0[2] = bf_lo(x4[1]) * rs * w0[2]; o0[3] = bf_hi(x4[1]) * rs * w0[3];
;                     o1[0] = bf_lo(x4[2]) * rs * w1[0]; o1[1] = bf_hi(x4[2]) * rs * w1[1]; o1[2] = bf_lo(x4[3]) * rs * w1[2]; o1[3] = bf_hi(x4[3]) * rs * w1[3];
;                     orow[2 * (lane + 64 * j)] = o0; orow[2 * (lane + 64 * j) + 1] = o1;
;                 }
;             }
;         }
.Lfn_e_p:
	s_lshl_b32 s18, s38, 12
	s_add_u32 s18, s4, s18
	s_addc_u32 s19, s5, 0
	v_cvt_f32_u32_e32 v66, v36
	v_cvt_f32_u32_e32 v67, v37
	v_fmamk_f32 v66, v67, 0x4f800000, v66
	v_fmamk_f32 v66, v66, 0x26800000, v4
	v_rsq_f32_e32 v64, v66
	v_lshlrev_b32_e32 v60, 16, v38
	v_and_b32_e32 v61, 0xffff0000, v38
	v_lshlrev_b32_e32 v62, 16, v39
	v_and_b32_e32 v63, 0xffff0000, v39
	v_pk_mul_f32 v[60:61], v[64:65], v[60:61] op_sel_hi:[0,1]
	v_pk_mul_f32 v[62:63], v[64:65], v[62:63] op_sel_hi:[0,1]
	v_pk_mul_f32 v[68:69], v[8:9], v[60:61]
	v_pk_mul_f32 v[70:71], v[10:11], v[62:63]
	global_store_dwordx4 v3, v[68:71], s[18:19] offset:0
	v_lshlrev_b32_e32 v60, 16, v40
	v_and_b32_e32 v61, 0xffff0000, v40
	v_lshlrev_b32_e32 v62, 16, v41
	v_and_b32_e32 v63, 0xffff0000, v41
	v_pk_mul_f32 v[60:61], v[64:65], v[60:61] op_sel_hi:[0,1]
	v_pk_mul_f32 v[62:63], v[64:65], v[62:63] op_sel_hi:[0,1]
	v_pk_mul_f32 v[72:73], v[12:13], v[60:61]
	v_pk_mul_f32 v[74:75], v[14:15], v[62:63]
	global_store_dwordx4 v3, v[72:75], s[18:19] offset:1024
	v_lshlrev_b32_e32 v60, 16, v42
	v_and_b32_e32 v61, 0xffff0000, v42
	v_lshlrev_b32_e32 v62, 16, v43
	v_and_b32_e32 v63, 0xffff0000, v43
	v_pk_mul_f32 v[60:61], v[64:65], v[60:61] op_sel_hi:[0,1]
	v_pk_mul_f32 v[62:63], v[64:65], v[62:63] op_sel_hi:[0,1]
	v_pk_mul_f32 v[76:77], v[16:17], v[60:61]
	v_pk_mul_f32 v[78:79], v[18:19], v[62:63]
	global_store_dwordx4 v3, v[76:79], s[18:19] offset:2048
	v_lshlrev_b32_e32 v60, 16, v44
	v_and_b32_e32 v61, 0xffff0000, v44
	v_lshlrev_b32_e32 v62, 16, v45
	v_and_b32_e32 v63, 0xffff0000, v45
	v_pk_mul_f32 v[60:61], v[64:65], v[60:61] op_sel_hi:[0,1]
	v_pk_mul_f32 v[62:63], v[64:65], v[62:63] op_sel_hi:[0,1]
	v_pk_mul_f32 v[80:81], v[20:21], v[60:61]
	v_pk_mul_f32 v[82:83], v[22:23], v[62:63]
	global_store_dwordx4 v3, v[80:83], s[18:19] offset:3072
	s_add_u32 s38, s38, s36
	s_cmp_lt_u32 s38, 0x1000
	s_cbranch_scc0 .LBB0_1445
	s_branch .Lfn_c
